# plus phase 0 transpose loop: vmcnt ladder recounted so the next-tile wait no longer drains the previous tile stores
# baseline (speedup 1.0000x reference)
; DI void ph_prologue(const Params& p, bf16_t* smem) {
;     ...
;     auto decode = [&](int it, const float*& sp, bf16_t*& dp, int& ld, int& K) {
;         const float* src; int N; bf16_t* dst; int t = it;
;         if (t < 768) { src = p.ew_in; ld = 3080; K = 1024; N = 3072; dst = (bf16_t*)(p.ws + OFF_W0IN); }
;         else if ((t -= 768) < 256) { src = p.ew_out; ld = 1024; K = 1024; N = 1024; dst = (bf16_t*)(p.ws + OFF_W0OUT); }
;         else if ((t -= 256) < 1536) { src = p.rw_in; ld = 6144; K = 1024; N = 6144; dst = (bf16_t*)(p.ws + OFF_W1IN); }
;         else if ((t -= 1536) < 512) { src = p.rw_out; ld = 1024; K = 2048; N = 1024; dst = (bf16_t*)(p.ws + OFF_W1OUT); }
;         else if ((t -= 512) < 2048) { const int l = t >> 10; t &= 1023; src = p.f_w1 + (size_t)l * 1024 * 4096; ld = 4096; K = 1024; N = 4096; dst = (bf16_t*)(p.ws + OFF_F1 + l * SZ_F); }
;         else { t -= 2048; const int l = t >> 10; t &= 1023; src = p.f_w2 + (size_t)l * 4096 * 1024; ld = 1024; K = 4096; N = 1024; dst = (bf16_t*)(p.ws + OFF_F2 + l * SZ_F); }
;         const int ntn = N >> 6, k0 = (t / ntn) * 64, n0 = (t % ntn) * 64;
;         sp = src + (size_t)k0 * ld + n0;
;         dp = dst + (size_t)n0 * K + k0;
;     };
;     {
;         const int tr = tid >> 6, tc = tid & 63;
;         int it = blockIdx.x;
;         const float* sp = nullptr; bf16_t* dp = nullptr; int ld = 0, K = 0;
;         float pre[8];
;         if (it < 7168) {
;             decode(it, sp, dp, ld, K);
; #pragma unroll
;             for (int i = 0; i < 8; ++i) pre[i] = sp[(size_t)(tr + 8 * i) * ld + tc];
;         }
.LBB0_39:
	v_cvt_f32_u32_e32 v0, s12
	s_sub_i32 s14, 0, s12
	s_abs_i32 s11, s13
	s_ashr_i32 s10, s13, 31
	v_rcp_iflag_f32_e32 v1, v0
	v_ashrrev_i32_e32 v0, 6, v4
	v_and_b32_e32 v2, 63, v4
	v_mov_b32_e32 v7, 0
	v_mul_f32_e32 v1, 0x4f7ffffe, v1
	v_cvt_u32_f32_e32 v1, v1
	v_lshlrev_b32_e32 v6, 2, v2
	v_mul_lo_u32 v5, s5, v0
	s_mov_b32 s34, s2
	v_readfirstlane_b32 s15, v1
	s_mul_i32 s14, s14, s15
	s_mul_hi_u32 s14, s15, s14
	s_add_i32 s15, s15, s14
	s_mul_hi_u32 s14, s11, s15
	s_mul_i32 s15, s14, s12
	s_sub_i32 s11, s11, s15
	s_add_i32 s16, s14, 1
	s_sub_i32 s15, s11, s12
	s_cmp_ge_u32 s11, s12
	s_cselect_b32 s14, s16, s14
	s_cselect_b32 s11, s15, s11
	s_add_i32 s15, s14, 1
	s_cmp_ge_u32 s11, s12
	s_cselect_b32 s11, s15, s14
	s_xor_b32 s11, s11, s10
	s_sub_i32 s14, s11, s10
	s_mul_i32 s10, s14, s12
	s_sub_i32 s10, s13, s10
	s_lshl_b32 s10, s10, 6
	s_ashr_i32 s11, s10, 31
	s_mul_hi_u32 s12, s8, s10
	s_mul_i32 s13, s8, s11
	s_mul_i32 s9, s9, s10
	s_add_i32 s12, s12, s13
	s_add_i32 s9, s12, s9
	s_mul_i32 s8, s8, s10
	s_lshl_b64 s[8:9], s[8:9], 1
	s_add_u32 s12, s0, s8
	s_addc_u32 s13, s1, s9
	s_lshl_b32 s8, s14, 6
	s_ashr_i32 s9, s8, 31
	s_lshl_b64 s[0:1], s[8:9], 1
	s_add_u32 s0, s12, s0
	s_mul_i32 s9, s4, s9
	s_mul_hi_u32 s12, s4, s8
	s_addc_u32 s1, s13, s1
	s_add_i32 s9, s12, s9
	s_mul_i32 s12, s5, s8
	s_add_i32 s9, s9, s12
	s_mul_i32 s8, s4, s8
	s_lshl_b64 s[8:9], s[8:9], 2
	s_add_u32 s8, s6, s8
	s_addc_u32 s9, s7, s9
	s_lshl_b64 s[6:7], s[10:11], 2
	s_add_u32 s6, s8, s6
	s_addc_u32 s7, s9, s7
	v_ashrrev_i32_e32 v1, 31, v0
	v_lshl_add_u64 v[22:23], s[6:7], 0, v[6:7]
	v_mul_lo_u32 v3, s4, v1
	v_mad_u64_u32 v[8:9], s[6:7], s4, v0, 0
	v_add3_u32 v9, v9, v3, v5
	v_lshl_add_u64 v[30:31], v[8:9], 2, v[22:23]
	v_add_u32_e32 v8, 8, v0
	v_ashrrev_i32_e32 v3, 31, v8
	v_mul_lo_u32 v5, s4, v3
	v_mul_lo_u32 v9, s5, v8
	v_mad_u64_u32 v[10:11], s[6:7], s4, v8, 0
	v_add3_u32 v11, v11, v5, v9
	v_lshl_add_u64 v[32:33], v[10:11], 2, v[22:23]
	v_add_u32_e32 v10, 16, v0
	v_ashrrev_i32_e32 v5, 31, v10
	v_mul_lo_u32 v9, s4, v5
	v_mul_lo_u32 v11, s5, v10
	v_mad_u64_u32 v[12:13], s[6:7], s4, v10, 0
	v_add3_u32 v13, v13, v9, v11
	v_lshl_add_u64 v[34:35], v[12:13], 2, v[22:23]
	v_add_u32_e32 v12, 24, v0
	v_ashrrev_i32_e32 v9, 31, v12
	v_mul_lo_u32 v11, s4, v9
	v_mul_lo_u32 v13, s5, v12
	v_mad_u64_u32 v[14:15], s[6:7], s4, v12, 0
	v_add3_u32 v15, v15, v11, v13
	v_lshl_add_u64 v[36:37], v[14:15], 2, v[22:23]
	v_add_u32_e32 v14, 32, v0
	v_ashrrev_i32_e32 v11, 31, v14
	v_mul_lo_u32 v13, s4, v11
	v_mul_lo_u32 v15, s5, v14
	v_mad_u64_u32 v[16:17], s[6:7], s4, v14, 0
	v_add3_u32 v17, v17, v13, v15
	v_lshl_add_u64 v[38:39], v[16:17], 2, v[22:23]
	v_add_u32_e32 v16, 40, v0
	v_ashrrev_i32_e32 v13, 31, v16
	v_mul_lo_u32 v15, s4, v13
	v_mul_lo_u32 v17, s5, v16
	v_mad_u64_u32 v[18:19], s[6:7], s4, v16, 0
	v_add3_u32 v19, v19, v15, v17
	v_lshl_add_u64 v[40:41], v[18:19], 2, v[22:23]
	v_add_u32_e32 v18, 48, v0
	v_ashrrev_i32_e32 v15, 31, v18
	v_mul_lo_u32 v17, s4, v15
	v_mul_lo_u32 v19, s5, v18
	v_mad_u64_u32 v[20:21], s[6:7], s4, v18, 0
	v_add3_u32 v21, v21, v17, v19
	v_lshl_add_u64 v[42:43], v[20:21], 2, v[22:23]
	v_add_u32_e32 v20, 56, v0
	v_ashrrev_i32_e32 v17, 31, v20
	v_mul_lo_u32 v19, s4, v17
	v_mul_lo_u32 v21, s5, v20
	v_mad_u64_u32 v[24:25], s[4:5], s4, v20, 0
	v_add3_u32 v25, v25, v19, v21
	v_lshl_add_u64 v[44:45], v[24:25], 2, v[22:23]
	global_load_dword v22, v[30:31], off
	global_load_dword v23, v[32:33], off
	global_load_dword v24, v[34:35], off
	global_load_dword v25, v[36:37], off
	global_load_dword v26, v[38:39], off
	global_load_dword v27, v[40:41], off
	global_load_dword v28, v[42:43], off
	global_load_dword v29, v[44:45], off
	s_add_u32 s26, s56, 0x2800000
	s_addc_u32 s27, s57, 0
	s_add_u32 s28, s56, 0x1800000
	s_addc_u32 s29, s57, 0
	s_add_u32 s6, s56, 0x1400000
	s_addc_u32 s7, s57, 0
	s_add_u32 s8, s56, 0x800000
	s_movk_i32 s4, 0x104
	s_addc_u32 s9, s57, 0
	v_lshl_add_u32 v21, v0, 2, 0
	v_add_u32_e32 v6, 0, v6
	v_mul_u32_u24_e32 v30, 0x104, v2
	v_mul_lo_u32 v19, v0, s4
	s_add_u32 s10, s56, 0x600000
	s_mov_b32 s5, 0
	s_addc_u32 s11, s57, 0
	v_add_u32_e32 v19, v6, v19
	v_add_u32_e32 v21, v21, v30
	s_mov_b32 s4, s3
	s_mov_b64 s[14:15], s[0:1]
	s_waitcnt vmcnt(0)
	s_branch .LBB0_43

; DI void ph_prologue(const Params& p, bf16_t* smem) {
;     ...
;         if (t < 768) { src = p.ew_in; ld = 3080; K = 1024; N = 3072; dst = (bf16_t*)(p.ws + OFF_W0IN); }
;         else if ((t -= 768) < 256) { src = p.ew_out; ld = 1024; K = 1024; N = 1024; dst = (bf16_t*)(p.ws + OFF_W0OUT); }
;         else if ((t -= 256) < 1536) { src = p.rw_in; ld = 6144; K = 1024; N = 6144; dst = (bf16_t*)(p.ws + OFF_W1IN); }
;         else if ((t -= 1536) < 512) { src = p.rw_out; ld = 1024; K = 2048; N = 1024; dst = (bf16_t*)(p.ws + OFF_W1OUT); }
;         else if ((t -= 512) < 2048) { const int l = t >> 10; t &= 1023; src = p.f_w1 + (size_t)l * 1024 * 4096; ld = 4096; K = 1024; N = 4096; dst = (bf16_t*)(p.ws + OFF_F1 + l * SZ_F); }
;         else { t -= 2048; const int l = t >> 10; t &= 1023; src = p.f_w2 + (size_t)l * 4096 * 1024; ld = 1024; K = 4096; N = 1024; dst = (bf16_t*)(p.ws + OFF_F2 + l * SZ_F); }
;     ...
;         while (it < 7168) {
; #pragma unroll
;             for (int i = 0; i < 8; ++i) tile[(tr + 8 * i) * 65 + tc] = pre[i];
;             __syncthreads();
;             bf16_t* dcur = dp; const int Kcur = K;
;             const int itn = it + (int)gridDim.x;
;             if (itn < 7168) {
;                 decode(itn, sp, dp, ld, K);
.LBB0_43:
	s_add_i32 s34, s34, s58
	s_cmpk_gt_i32 s34, 0x1bff
	s_cselect_b64 s[12:13], -1, 0
	s_and_b64 vcc, exec, s[12:13]
	s_waitcnt vmcnt(15)
	ds_write_b32 v19, v22
	s_waitcnt vmcnt(14)
	ds_write_b32 v19, v23 offset:2080
	s_waitcnt vmcnt(13)
	ds_write_b32 v19, v24 offset:4160
	s_waitcnt vmcnt(12)
	ds_write_b32 v19, v25 offset:6240
	s_waitcnt vmcnt(11)
	ds_write_b32 v19, v26 offset:8320
	s_waitcnt vmcnt(10)
	ds_write_b32 v19, v27 offset:10400
	s_waitcnt vmcnt(9)
	ds_write_b32 v19, v28 offset:12480
	s_waitcnt vmcnt(8)
	ds_write_b32 v19, v29 offset:14560
	s_waitcnt lgkmcnt(0)
	s_barrier
	s_cbranch_vccnz .LBB0_42
	s_cmpk_lt_i32 s34, 0x300
	s_cbranch_scc1 .LBB0_40
	s_cmpk_gt_u32 s34, 0x3ff
	s_cbranch_scc0 .LBB0_52
	s_cmpk_gt_u32 s34, 0x9ff
	s_cbranch_scc0 .LBB0_53
	s_cmpk_gt_u32 s34, 0xbff
	s_cbranch_scc0 .LBB0_54
	s_cmpk_gt_u32 s34, 0x13ff
	s_mov_b64 s[16:17], -1
	s_cbranch_scc0 .LBB0_50
	s_add_i32 s4, s34, 0xffffec00
	s_lshr_b32 s4, s4, 10
	s_lshl_b64 s[14:15], s[4:5], 24
	s_add_u32 s20, s52, s14
	s_addc_u32 s21, s53, s15
	s_lshl_b64 s[14:15], s[4:5], 23
	s_add_u32 s14, s26, s14
	s_addc_u32 s15, s27, s15
	s_mov_b64 s[16:17], 0
